# deferred phase-0 items rebalanced: GluT/WoutT transposes and the last 256 cpow/misc pairs now run on workgroups 192..255 in phase 3 after their conv item (idle there), phase-2 tail keeps the rest
# speedup vs baseline: 1.0531x; 1.0045x over previous
_Z11mega_kernel6Params:
	s_load_dwordx16 s[4:19], s[0:1], 0xc0
	s_mov_b32 s81, s2
	s_load_dwordx8 s[84:91], s[0:1], 0x100
	s_load_dword s2, s[0:1], 0x168
	s_load_dwordx4 s[92:95], s[0:1], 0x120
	s_load_dwordx2 s[82:83], s[0:1], 0x160
	s_add_u32 s78, s0, 0x160
	s_waitcnt lgkmcnt(0)
	v_writelane_b32 v241, s4, 0
	v_and_b32_e32 v193, 0x3ff, v0
	s_addc_u32 s79, s1, 0
	v_writelane_b32 v250, s78, 0
	v_writelane_b32 v250, s79, 1
	v_writelane_b32 v241, s5, 1
	v_writelane_b32 v241, s6, 2
	v_writelane_b32 v241, s7, 3
	v_writelane_b32 v241, s8, 4
	v_writelane_b32 v241, s9, 5
	v_writelane_b32 v241, s10, 6
	v_writelane_b32 v241, s11, 7
	v_writelane_b32 v241, s12, 8
	v_writelane_b32 v241, s13, 9
	v_writelane_b32 v241, s14, 10
	v_writelane_b32 v241, s15, 11
	v_writelane_b32 v241, s16, 12
	v_writelane_b32 v241, s17, 13
	v_writelane_b32 v241, s18, 14
	v_writelane_b32 v241, s19, 15
	v_cmp_eq_u32_e64 s[96:97], 0, v193
	v_writelane_b32 v241, s2, 16
	s_and_saveexec_b64 s[4:5], s[96:97]
	s_cbranch_execz .LBB0_2
	s_add_i32 s2, 0, 0x20010
	v_mov_b32_e32 v1, 0
	v_mov_b32_e32 v2, s2
	s_add_i32 s2, 0, 0x20014
	ds_write_b32 v2, v1
	v_mov_b32_e32 v2, s2
	ds_write_b32 v2, v1

.LBB0_92:
	s_load_dwordx2 s[6:7], s[0:1], 0x158
	s_load_dwordx8 s[36:43], s[0:1], 0x138
	s_cmp_eq_u32 s101, 0
	s_cbranch_scc1 .Lst_cont0
	s_waitcnt lgkmcnt(0)
	s_cmp_eq_u32 s101, 2
	s_cbranch_scc1 .Lst_b_to_p1
	s_cmp_eq_u32 s101, 5
	s_cbranch_scc1 .Lst_p2tail
	s_cmp_ge_u32 s101, 6
	s_cbranch_scc1 .Lst_p3tail
	s_cmpk_lg_i32 s82, 0x100
	s_cselect_b64 s[0:1], -1, 0
	v_writelane_b32 v240, s0, 11
	v_writelane_b32 v240, s1, 12
	s_cmp_lt_i32 s81, 32
	s_cselect_b64 s[0:1], -1, 0
	s_branch .LBB0_179

.Lst_p3tail:
	s_cmp_eq_u32 s101, 7
	s_cbranch_scc1 .Lst_p3tail2
	s_mov_b32 s101, 7
	s_mov_b32 s98, 64
	s_sub_u32 s99, s81, 0xc0
	s_add_u32 s99, s99, 0xe81
	s_mov_b32 s100, 0xf81
	s_branch .Lp0_enter

.LBB0_251:
	v_mov_b32_e32 v8, v193
	s_andn2_b64 vcc, exec, s[0:1]
	v_readfirstlane_b32 s2, v8
	s_cbranch_vccz .Lctx_unit
	s_cmpk_lg_i32 s82, 0x100
	s_cbranch_scc1 .LBB0_262
	s_mov_b32 s101, 5
	s_mov_b32 s98, 0xe0
	s_sub_u32 s99, s81, 32
	s_add_u32 s99, s99, 0x560
	s_mov_b32 s100, 0xe81
	s_sub_u32 s0, s78, 0x160
	s_subb_u32 s1, s79, 0
	s_branch .Lp0_enter
.Lp0_tramp:
	s_branch .Lp0_enter

.LBB0_404:
	s_waitcnt vmcnt(0)
	s_waitcnt vmcnt(0) lgkmcnt(0)
	s_barrier
	s_cmp_ge_u32 s101, 6
	s_cbranch_scc1 .Lp3_items_done
	s_cmpk_lt_i32 s81, 0xc0
	s_cbranch_scc1 .Lp3_items_done
	s_cmpk_lg_i32 s82, 0x100
	s_cbranch_scc1 .Lp3_items_done
	s_mov_b32 s101, 6
	s_mov_b32 s98, 64
	s_sub_u32 s99, s81, 0xc0
	s_add_u32 s99, s99, 0x3e0
	s_mov_b32 s100, 0x560
	v_readlane_b32 s78, v250, 0
	v_readlane_b32 s79, v250, 1
	s_nop 1
	s_sub_u32 s0, s78, 0x160
	s_subb_u32 s1, s79, 0
	s_branch .Lp0_tramp
